# combined: mu hoist + P1 bias epilogue de-serialised + P0 transpose loads batched (each small on its own)
# baseline (speedup 1.0000x reference)
.LBB0_1758:
	v_readfirstlane_b32 s8, v126
	v_readfirstlane_b32 s4, v125
	s_lshl_b32 s8, s8, 6
	s_add_i32 s8, s8, s34
	s_lshl_b32 s4, s4, 6
	s_waitcnt vmcnt(9)
	v_or_b32_e32 v64, s8, v127
	s_add_i32 s4, s4, s15
	s_waitcnt vmcnt(8)
	v_or_b32_e32 v69, s4, v129
	v_cmp_gt_i32_e32 vcc, s69, v64
	v_ashrrev_i32_e32 v65, 31, v64
	s_waitcnt lgkmcnt(0)
	s_barrier
	s_waitcnt vmcnt(0)
	s_mov_b64 s[8:9], exec
	s_mov_b64 s[40:41], vcc
	v_or_b32_e32 v66, 32, v64
	v_cmp_gt_i32_e64 s[38:39], s69, v66
	v_lshlrev_b32_e32 v66, 2, v64
	s_and_b64 exec, s[8:9], s[40:41]
	global_load_dword v67, v66, s[30:31]
	s_and_b64 exec, s[8:9], s[38:39]
	global_load_dword v68, v66, s[30:31] offset:128
	s_mov_b64 exec, s[8:9]
	v_mul_u32_u24_e32 v70, 0xc000, v69
	v_lshl_add_u32 v70, v64, 2, v70
	s_waitcnt vmcnt(0)
	s_and_b64 s[34:35], s[8:9], s[40:41]
	s_mov_b64 exec, s[34:35]
	v_cmp_gt_i32_e32 vcc, 0x84, v69
	s_and_b64 exec, s[34:35], vcc
	v_add_f32_e32 v48, v48, v67
	global_store_dword v70, v48, s[28:29]
	s_mov_b64 exec, s[34:35]
	v_cmp_gt_i32_e32 vcc, 0x83, v69
	s_and_b64 exec, s[34:35], vcc
	v_add_f32_e32 v49, v49, v67
	v_add_u32_e32 v71, 0xc000, v70
	global_store_dword v71, v49, s[28:29]
	s_mov_b64 exec, s[34:35]
	v_cmp_gt_i32_e32 vcc, 0x82, v69
	s_and_b64 exec, s[34:35], vcc
	v_add_f32_e32 v50, v50, v67
	v_add_u32_e32 v72, 0x18000, v70
	global_store_dword v72, v50, s[28:29]
	s_mov_b64 exec, s[34:35]
	v_cmp_gt_i32_e32 vcc, 0x81, v69
	s_and_b64 exec, s[34:35], vcc
	v_add_f32_e32 v51, v51, v67
	v_add_u32_e32 v73, 0x24000, v70
	global_store_dword v73, v51, s[28:29]
	s_mov_b64 exec, s[34:35]
	v_cmp_gt_i32_e32 vcc, 0x7c, v69
	s_and_b64 exec, s[34:35], vcc
	v_add_f32_e32 v52, v52, v67
	v_add_u32_e32 v71, 0x60000, v70
	global_store_dword v71, v52, s[28:29]
	s_mov_b64 exec, s[34:35]
	v_cmp_gt_i32_e32 vcc, 0x7b, v69
	s_and_b64 exec, s[34:35], vcc
	v_add_f32_e32 v53, v53, v67
	v_add_u32_e32 v72, 0x6c000, v70
	global_store_dword v72, v53, s[28:29]
	s_mov_b64 exec, s[34:35]
	v_cmp_gt_i32_e32 vcc, 0x7a, v69
	s_and_b64 exec, s[34:35], vcc
	v_add_f32_e32 v54, v54, v67
	v_add_u32_e32 v73, 0x78000, v70
	global_store_dword v73, v54, s[28:29]
	s_mov_b64 exec, s[34:35]
	v_cmp_gt_i32_e32 vcc, 0x79, v69
	s_and_b64 exec, s[34:35], vcc
	v_add_f32_e32 v55, v55, v67
	v_add_u32_e32 v71, 0x84000, v70
	global_store_dword v71, v55, s[28:29]
	s_mov_b64 exec, s[34:35]
	v_cmp_gt_i32_e32 vcc, 0x74, v69
	s_and_b64 exec, s[34:35], vcc
	v_add_f32_e32 v56, v56, v67
	v_add_u32_e32 v72, 0xc0000, v70
	global_store_dword v72, v56, s[28:29]
	s_mov_b64 exec, s[34:35]
	v_cmp_gt_i32_e32 vcc, 0x73, v69
	s_and_b64 exec, s[34:35], vcc
	v_add_f32_e32 v57, v57, v67
	v_add_u32_e32 v73, 0xcc000, v70
	global_store_dword v73, v57, s[28:29]
	s_mov_b64 exec, s[34:35]
	v_cmp_gt_i32_e32 vcc, 0x72, v69
	s_and_b64 exec, s[34:35], vcc
	v_add_f32_e32 v58, v58, v67
	v_add_u32_e32 v71, 0xd8000, v70
	global_store_dword v71, v58, s[28:29]
	s_mov_b64 exec, s[34:35]
	v_cmp_gt_i32_e32 vcc, 0x71, v69
	s_and_b64 exec, s[34:35], vcc
	v_add_f32_e32 v59, v59, v67
	v_add_u32_e32 v72, 0xe4000, v70
	global_store_dword v72, v59, s[28:29]
	s_mov_b64 exec, s[34:35]
	v_cmp_gt_i32_e32 vcc, 0x6c, v69
	s_and_b64 exec, s[34:35], vcc
	v_add_f32_e32 v60, v60, v67
	v_add_u32_e32 v73, 0x120000, v70
	global_store_dword v73, v60, s[28:29]
	s_mov_b64 exec, s[34:35]
	v_cmp_gt_i32_e32 vcc, 0x6b, v69
	s_and_b64 exec, s[34:35], vcc
	v_add_f32_e32 v61, v61, v67
	v_add_u32_e32 v71, 0x12c000, v70
	global_store_dword v71, v61, s[28:29]
	s_mov_b64 exec, s[34:35]
	v_cmp_gt_i32_e32 vcc, 0x6a, v69
	s_and_b64 exec, s[34:35], vcc
	v_add_f32_e32 v62, v62, v67
	v_add_u32_e32 v72, 0x138000, v70
	global_store_dword v72, v62, s[28:29]
	s_mov_b64 exec, s[34:35]
	v_cmp_gt_i32_e32 vcc, 0x69, v69
	s_and_b64 exec, s[34:35], vcc
	v_add_f32_e32 v63, v63, v67
	v_add_u32_e32 v73, 0x144000, v70
	global_store_dword v73, v63, s[28:29]
	s_and_b64 s[34:35], s[8:9], s[38:39]
	s_mov_b64 exec, s[34:35]
	v_cmp_gt_i32_e32 vcc, 0x84, v69
	s_and_b64 exec, s[34:35], vcc
	v_add_f32_e32 v32, v32, v68
	global_store_dword v70, v32, s[28:29] offset:128
	s_mov_b64 exec, s[34:35]
	v_cmp_gt_i32_e32 vcc, 0x83, v69
	s_and_b64 exec, s[34:35], vcc
	v_add_f32_e32 v33, v33, v68
	v_add_u32_e32 v71, 0xc000, v70
	global_store_dword v71, v33, s[28:29] offset:128
	s_mov_b64 exec, s[34:35]
	v_cmp_gt_i32_e32 vcc, 0x82, v69
	s_and_b64 exec, s[34:35], vcc
	v_add_f32_e32 v34, v34, v68
	v_add_u32_e32 v72, 0x18000, v70
	global_store_dword v72, v34, s[28:29] offset:128
	s_mov_b64 exec, s[34:35]
	v_cmp_gt_i32_e32 vcc, 0x81, v69
	s_and_b64 exec, s[34:35], vcc
	v_add_f32_e32 v35, v35, v68
	v_add_u32_e32 v73, 0x24000, v70
	global_store_dword v73, v35, s[28:29] offset:128
	s_mov_b64 exec, s[34:35]
	v_cmp_gt_i32_e32 vcc, 0x7c, v69
	s_and_b64 exec, s[34:35], vcc
	v_add_f32_e32 v36, v36, v68
	v_add_u32_e32 v71, 0x60000, v70
	global_store_dword v71, v36, s[28:29] offset:128
	s_mov_b64 exec, s[34:35]
	v_cmp_gt_i32_e32 vcc, 0x7b, v69
	s_and_b64 exec, s[34:35], vcc
	v_add_f32_e32 v37, v37, v68
	v_add_u32_e32 v72, 0x6c000, v70
	global_store_dword v72, v37, s[28:29] offset:128
	s_mov_b64 exec, s[34:35]
	v_cmp_gt_i32_e32 vcc, 0x7a, v69
	s_and_b64 exec, s[34:35], vcc
	v_add_f32_e32 v38, v38, v68
	v_add_u32_e32 v73, 0x78000, v70
	global_store_dword v73, v38, s[28:29] offset:128
	s_mov_b64 exec, s[34:35]
	v_cmp_gt_i32_e32 vcc, 0x79, v69
	s_and_b64 exec, s[34:35], vcc
	v_add_f32_e32 v39, v39, v68
	v_add_u32_e32 v71, 0x84000, v70
	global_store_dword v71, v39, s[28:29] offset:128
	s_mov_b64 exec, s[34:35]
	v_cmp_gt_i32_e32 vcc, 0x74, v69
	s_and_b64 exec, s[34:35], vcc
	v_add_f32_e32 v40, v40, v68
	v_add_u32_e32 v72, 0xc0000, v70
	global_store_dword v72, v40, s[28:29] offset:128
	s_mov_b64 exec, s[34:35]
	v_cmp_gt_i32_e32 vcc, 0x73, v69
	s_and_b64 exec, s[34:35], vcc
	v_add_f32_e32 v41, v41, v68
	v_add_u32_e32 v73, 0xcc000, v70
	global_store_dword v73, v41, s[28:29] offset:128
	s_mov_b64 exec, s[34:35]
	v_cmp_gt_i32_e32 vcc, 0x72, v69
	s_and_b64 exec, s[34:35], vcc
	v_add_f32_e32 v42, v42, v68
	v_add_u32_e32 v71, 0xd8000, v70
	global_store_dword v71, v42, s[28:29] offset:128
	s_mov_b64 exec, s[34:35]
	v_cmp_gt_i32_e32 vcc, 0x71, v69
	s_and_b64 exec, s[34:35], vcc
	v_add_f32_e32 v43, v43, v68
	v_add_u32_e32 v72, 0xe4000, v70
	global_store_dword v72, v43, s[28:29] offset:128
	s_mov_b64 exec, s[34:35]
	v_cmp_gt_i32_e32 vcc, 0x6c, v69
	s_and_b64 exec, s[34:35], vcc
	v_add_f32_e32 v44, v44, v68
	v_add_u32_e32 v73, 0x120000, v70
	global_store_dword v73, v44, s[28:29] offset:128
	s_mov_b64 exec, s[34:35]
	v_cmp_gt_i32_e32 vcc, 0x6b, v69
	s_and_b64 exec, s[34:35], vcc
	v_add_f32_e32 v45, v45, v68
	v_add_u32_e32 v71, 0x12c000, v70
	global_store_dword v71, v45, s[28:29] offset:128
	s_mov_b64 exec, s[34:35]
	v_cmp_gt_i32_e32 vcc, 0x6a, v69
	s_and_b64 exec, s[34:35], vcc
	v_add_f32_e32 v46, v46, v68
	v_add_u32_e32 v72, 0x138000, v70
	global_store_dword v72, v46, s[28:29] offset:128
	s_mov_b64 exec, s[34:35]
	v_cmp_gt_i32_e32 vcc, 0x69, v69
	s_and_b64 exec, s[34:35], vcc
	v_add_f32_e32 v47, v47, v68
	v_add_u32_e32 v73, 0x144000, v70
	global_store_dword v73, v47, s[28:29] offset:128
	s_and_b64 s[34:35], s[8:9], s[40:41]
	s_mov_b64 exec, s[34:35]
	v_cmp_gt_i32_e32 vcc, 0x64, v69
	s_and_b64 exec, s[34:35], vcc
	v_add_f32_e32 v16, v16, v67
	v_add_u32_e32 v71, 0x180000, v70
	global_store_dword v71, v16, s[28:29]
	s_mov_b64 exec, s[34:35]
	v_cmp_gt_i32_e32 vcc, 0x63, v69
	s_and_b64 exec, s[34:35], vcc
	v_add_f32_e32 v17, v17, v67
	v_add_u32_e32 v72, 0x18c000, v70
	global_store_dword v72, v17, s[28:29]
	s_mov_b64 exec, s[34:35]
	v_cmp_gt_i32_e32 vcc, 0x62, v69
	s_and_b64 exec, s[34:35], vcc
	v_add_f32_e32 v18, v18, v67
	v_add_u32_e32 v73, 0x198000, v70
	global_store_dword v73, v18, s[28:29]
	s_mov_b64 exec, s[34:35]
	v_cmp_gt_i32_e32 vcc, 0x61, v69
	s_and_b64 exec, s[34:35], vcc
	v_add_f32_e32 v19, v19, v67
	v_add_u32_e32 v71, 0x1a4000, v70
	global_store_dword v71, v19, s[28:29]
	s_mov_b64 exec, s[34:35]
	v_cmp_gt_i32_e32 vcc, 0x5c, v69
	s_and_b64 exec, s[34:35], vcc
	v_add_f32_e32 v20, v20, v67
	v_add_u32_e32 v72, 0x1e0000, v70
	global_store_dword v72, v20, s[28:29]
	s_mov_b64 exec, s[34:35]
	v_cmp_gt_i32_e32 vcc, 0x5b, v69
	s_and_b64 exec, s[34:35], vcc
	v_add_f32_e32 v21, v21, v67
	v_add_u32_e32 v73, 0x1ec000, v70
	global_store_dword v73, v21, s[28:29]
	s_mov_b64 exec, s[34:35]
	v_cmp_gt_i32_e32 vcc, 0x5a, v69
	s_and_b64 exec, s[34:35], vcc
	v_add_f32_e32 v22, v22, v67
	v_add_u32_e32 v71, 0x1f8000, v70
	global_store_dword v71, v22, s[28:29]
	s_mov_b64 exec, s[34:35]
	v_cmp_gt_i32_e32 vcc, 0x59, v69
	s_and_b64 exec, s[34:35], vcc
	v_add_f32_e32 v23, v23, v67
	v_add_u32_e32 v72, 0x204000, v70
	global_store_dword v72, v23, s[28:29]
	s_mov_b64 exec, s[34:35]
	v_cmp_gt_i32_e32 vcc, 0x54, v69
	s_and_b64 exec, s[34:35], vcc
	v_add_f32_e32 v24, v24, v67
	v_add_u32_e32 v73, 0x240000, v70
	global_store_dword v73, v24, s[28:29]
	s_mov_b64 exec, s[34:35]
	v_cmp_gt_i32_e32 vcc, 0x53, v69
	s_and_b64 exec, s[34:35], vcc
	v_add_f32_e32 v25, v25, v67
	v_add_u32_e32 v71, 0x24c000, v70
	global_store_dword v71, v25, s[28:29]
	s_mov_b64 exec, s[34:35]
	v_cmp_gt_i32_e32 vcc, 0x52, v69
	s_and_b64 exec, s[34:35], vcc
	v_add_f32_e32 v26, v26, v67
	v_add_u32_e32 v72, 0x258000, v70
	global_store_dword v72, v26, s[28:29]
	s_mov_b64 exec, s[34:35]
	v_cmp_gt_i32_e32 vcc, 0x51, v69
	s_and_b64 exec, s[34:35], vcc
	v_add_f32_e32 v27, v27, v67
	v_add_u32_e32 v73, 0x264000, v70
	global_store_dword v73, v27, s[28:29]
	s_mov_b64 exec, s[34:35]
	v_cmp_gt_i32_e32 vcc, 0x4c, v69
	s_and_b64 exec, s[34:35], vcc
	v_add_f32_e32 v28, v28, v67
	v_add_u32_e32 v71, 0x2a0000, v70
	global_store_dword v71, v28, s[28:29]
	s_mov_b64 exec, s[34:35]
	v_cmp_gt_i32_e32 vcc, 0x4b, v69
	s_and_b64 exec, s[34:35], vcc
	v_add_f32_e32 v29, v29, v67
	v_add_u32_e32 v72, 0x2ac000, v70
	global_store_dword v72, v29, s[28:29]
	s_mov_b64 exec, s[34:35]
	v_cmp_gt_i32_e32 vcc, 0x4a, v69
	s_and_b64 exec, s[34:35], vcc
	v_add_f32_e32 v30, v30, v67
	v_add_u32_e32 v73, 0x2b8000, v70
	global_store_dword v73, v30, s[28:29]
	s_mov_b64 exec, s[34:35]
	v_cmp_gt_i32_e32 vcc, 0x49, v69
	s_and_b64 exec, s[34:35], vcc
	v_add_f32_e32 v31, v31, v67
	v_add_u32_e32 v71, 0x2c4000, v70
	global_store_dword v71, v31, s[28:29]
	s_and_b64 s[34:35], s[8:9], s[38:39]
	s_mov_b64 exec, s[34:35]
	v_cmp_gt_i32_e32 vcc, 0x64, v69
	s_and_b64 exec, s[34:35], vcc
	v_add_f32_e32 v0, v0, v68
	v_add_u32_e32 v72, 0x180000, v70
	global_store_dword v72, v0, s[28:29] offset:128
	s_mov_b64 exec, s[34:35]
	v_cmp_gt_i32_e32 vcc, 0x63, v69
	s_and_b64 exec, s[34:35], vcc
	v_add_f32_e32 v1, v1, v68
	v_add_u32_e32 v73, 0x18c000, v70
	global_store_dword v73, v1, s[28:29] offset:128
	s_mov_b64 exec, s[34:35]
	v_cmp_gt_i32_e32 vcc, 0x62, v69
	s_and_b64 exec, s[34:35], vcc
	v_add_f32_e32 v2, v2, v68
	v_add_u32_e32 v71, 0x198000, v70
	global_store_dword v71, v2, s[28:29] offset:128
	s_mov_b64 exec, s[34:35]
	v_cmp_gt_i32_e32 vcc, 0x61, v69
	s_and_b64 exec, s[34:35], vcc
	v_add_f32_e32 v3, v3, v68
	v_add_u32_e32 v72, 0x1a4000, v70
	global_store_dword v72, v3, s[28:29] offset:128
	s_mov_b64 exec, s[34:35]
	v_cmp_gt_i32_e32 vcc, 0x5c, v69
	s_and_b64 exec, s[34:35], vcc
	v_add_f32_e32 v4, v4, v68
	v_add_u32_e32 v73, 0x1e0000, v70
	global_store_dword v73, v4, s[28:29] offset:128
	s_mov_b64 exec, s[34:35]
	v_cmp_gt_i32_e32 vcc, 0x5b, v69
	s_and_b64 exec, s[34:35], vcc
	v_add_f32_e32 v5, v5, v68
	v_add_u32_e32 v71, 0x1ec000, v70
	global_store_dword v71, v5, s[28:29] offset:128
	s_mov_b64 exec, s[34:35]
	v_cmp_gt_i32_e32 vcc, 0x5a, v69
	s_and_b64 exec, s[34:35], vcc
	v_add_f32_e32 v6, v6, v68
	v_add_u32_e32 v72, 0x1f8000, v70
	global_store_dword v72, v6, s[28:29] offset:128
	s_mov_b64 exec, s[34:35]
	v_cmp_gt_i32_e32 vcc, 0x59, v69
	s_and_b64 exec, s[34:35], vcc
	v_add_f32_e32 v7, v7, v68
	v_add_u32_e32 v73, 0x204000, v70
	global_store_dword v73, v7, s[28:29] offset:128
	s_mov_b64 exec, s[34:35]
	v_cmp_gt_i32_e32 vcc, 0x54, v69
	s_and_b64 exec, s[34:35], vcc
	v_add_f32_e32 v8, v8, v68
	v_add_u32_e32 v71, 0x240000, v70
	global_store_dword v71, v8, s[28:29] offset:128
	s_mov_b64 exec, s[34:35]
	v_cmp_gt_i32_e32 vcc, 0x53, v69
	s_and_b64 exec, s[34:35], vcc
	v_add_f32_e32 v9, v9, v68
	v_add_u32_e32 v72, 0x24c000, v70
	global_store_dword v72, v9, s[28:29] offset:128
	s_mov_b64 exec, s[34:35]
	v_cmp_gt_i32_e32 vcc, 0x52, v69
	s_and_b64 exec, s[34:35], vcc
	v_add_f32_e32 v10, v10, v68
	v_add_u32_e32 v73, 0x258000, v70
	global_store_dword v73, v10, s[28:29] offset:128
	s_mov_b64 exec, s[34:35]
	v_cmp_gt_i32_e32 vcc, 0x51, v69
	s_and_b64 exec, s[34:35], vcc
	v_add_f32_e32 v11, v11, v68
	v_add_u32_e32 v71, 0x264000, v70
	global_store_dword v71, v11, s[28:29] offset:128
	s_mov_b64 exec, s[34:35]
	v_cmp_gt_i32_e32 vcc, 0x4c, v69
	s_and_b64 exec, s[34:35], vcc
	v_add_f32_e32 v12, v12, v68
	v_add_u32_e32 v72, 0x2a0000, v70
	global_store_dword v72, v12, s[28:29] offset:128
	s_mov_b64 exec, s[34:35]
	v_cmp_gt_i32_e32 vcc, 0x4b, v69
	s_and_b64 exec, s[34:35], vcc
	v_add_f32_e32 v13, v13, v68
	v_add_u32_e32 v73, 0x2ac000, v70
	global_store_dword v73, v13, s[28:29] offset:128
	s_mov_b64 exec, s[34:35]
	v_cmp_gt_i32_e32 vcc, 0x4a, v69
	s_and_b64 exec, s[34:35], vcc
	v_add_f32_e32 v14, v14, v68
	v_add_u32_e32 v71, 0x2b8000, v70
	global_store_dword v71, v14, s[28:29] offset:128
	s_mov_b64 exec, s[34:35]
	v_cmp_gt_i32_e32 vcc, 0x49, v69
	s_and_b64 exec, s[34:35], vcc
	v_add_f32_e32 v15, v15, v68
	v_add_u32_e32 v72, 0x2c4000, v70
	global_store_dword v72, v15, s[28:29] offset:128
	s_branch .LBB0_1749
